# grid barrier: non-leader workgroups poll the cross-XCD release generation word directly instead of their XCD's forwarded release (arrival stays hierarchical), on top of the K-loop hand-off trim
# baseline (speedup 1.0000x reference)
.LBB0_748:
	s_or_b64 exec, exec, s[14:15]
	v_cvt_f32_u32_e32 v6, v4
	s_waitcnt vmcnt(0)
	v_readfirstlane_b32 s7, v5
	v_sub_u32_e32 v5, 0, v4
	v_rcp_iflag_f32_e32 v6, v6
	v_add_u32_e32 v7, s7, v3
	v_mul_f32_e32 v6, 0x4f7ffffe, v6
	v_cvt_u32_f32_e32 v6, v6
	v_mul_lo_u32 v3, v5, v6
	v_mul_hi_u32 v3, v6, v3
	v_add_u32_e32 v3, v6, v3
	v_mul_hi_u32 v3, v7, v3
	v_mul_lo_u32 v5, v3, v4
	v_sub_u32_e32 v5, v7, v5
	v_add_u32_e32 v6, 1, v3
	v_cmp_ge_u32_e32 vcc, v5, v4
	s_nop 1
	v_cndmask_b32_e32 v3, v3, v6, vcc
	v_sub_u32_e32 v6, v5, v4
	v_cndmask_b32_e32 v5, v5, v6, vcc
	v_add_u32_e32 v6, 1, v3
	v_cmp_ge_u32_e32 vcc, v5, v4
	v_add_u32_e32 v5, 1, v7
	s_nop 0
	v_cndmask_b32_e32 v3, v3, v6, vcc
	v_mul_lo_u32 v6, v4, v3
	v_add_u32_e32 v4, v6, v4
	v_cmp_ne_u32_e32 vcc, v5, v4
	s_and_saveexec_b64 s[8:9], vcc
	s_xor_b64 s[14:15], exec, s[8:9]
	s_cbranch_execz .LBB0_762
	v_readlane_b32 s8, v255, 10
	v_readlane_b32 s9, v255, 11
	s_waitcnt lgkmcnt(0)
	s_nop 3
	global_load_dword v2, v181, s[8:9] sc1
	s_waitcnt vmcnt(0)
	v_cmp_eq_u32_e32 vcc, v2, v3
	s_and_saveexec_b64 s[18:19], vcc
	s_cbranch_execz .LBB0_761
	s_mov_b32 s7, 1
	s_mov_b64 s[22:23], 0
	s_branch .LBB0_752

.LBB0_754:
	v_readlane_b32 s8, v255, 10
	v_readlane_b32 s9, v255, 11
	s_add_i32 s7, s7, 1
	s_mov_b64 s[28:29], -1
	s_nop 2
	global_load_dword v2, v181, s[8:9] sc1
	s_waitcnt vmcnt(0)
	v_cmp_ne_u32_e32 vcc, v2, v3
	s_orn2_b64 s[26:27], vcc, exec
	s_branch .LBB0_751

.LBB0_963:
	s_or_b64 exec, exec, s[14:15]
	v_cvt_f32_u32_e32 v6, v4
	s_waitcnt vmcnt(0)
	v_readfirstlane_b32 s6, v5
	v_sub_u32_e32 v5, 0, v4
	v_rcp_iflag_f32_e32 v6, v6
	v_add_u32_e32 v7, s6, v3
	v_mul_f32_e32 v6, 0x4f7ffffe, v6
	v_cvt_u32_f32_e32 v6, v6
	v_mul_lo_u32 v3, v5, v6
	v_mul_hi_u32 v3, v6, v3
	v_add_u32_e32 v3, v6, v3
	v_mul_hi_u32 v3, v7, v3
	v_mul_lo_u32 v5, v3, v4
	v_sub_u32_e32 v5, v7, v5
	v_add_u32_e32 v6, 1, v3
	v_cmp_ge_u32_e32 vcc, v5, v4
	s_nop 1
	v_cndmask_b32_e32 v3, v3, v6, vcc
	v_sub_u32_e32 v6, v5, v4
	v_cndmask_b32_e32 v5, v5, v6, vcc
	v_add_u32_e32 v6, 1, v3
	v_cmp_ge_u32_e32 vcc, v5, v4
	v_add_u32_e32 v5, 1, v7
	s_nop 0
	v_cndmask_b32_e32 v3, v3, v6, vcc
	v_mul_lo_u32 v6, v4, v3
	v_add_u32_e32 v4, v6, v4
	v_cmp_ne_u32_e32 vcc, v5, v4
	s_and_saveexec_b64 s[6:7], vcc
	s_xor_b64 s[14:15], exec, s[6:7]
	s_cbranch_execz .LBB0_977
	v_readlane_b32 s6, v255, 10
	v_readlane_b32 s7, v255, 11
	s_waitcnt lgkmcnt(0)
	s_nop 3
	global_load_dword v2, v181, s[6:7] sc1
	s_waitcnt vmcnt(0)
	v_cmp_eq_u32_e32 vcc, v2, v3
	s_and_saveexec_b64 s[18:19], vcc
	s_cbranch_execz .LBB0_976
	s_mov_b32 s6, 1
	s_mov_b64 s[22:23], 0
	s_branch .LBB0_967

.LBB0_969:
	v_readlane_b32 s8, v255, 10
	v_readlane_b32 s9, v255, 11
	s_add_i32 s6, s6, 1
	s_mov_b64 s[28:29], -1
	s_nop 2
	global_load_dword v2, v181, s[8:9] sc1
	s_waitcnt vmcnt(0)
	v_cmp_ne_u32_e32 vcc, v2, v3
	s_orn2_b64 s[26:27], vcc, exec
	s_branch .LBB0_966

.LBB0_1372:
	s_or_b64 exec, exec, s[18:19]
	v_cvt_f32_u32_e32 v6, v4
	s_waitcnt vmcnt(0)
	v_readfirstlane_b32 s7, v5
	v_sub_u32_e32 v5, 0, v4
	v_rcp_iflag_f32_e32 v6, v6
	v_add_u32_e32 v7, s7, v3
	v_mul_f32_e32 v6, 0x4f7ffffe, v6
	v_cvt_u32_f32_e32 v6, v6
	v_mul_lo_u32 v3, v5, v6
	v_mul_hi_u32 v3, v6, v3
	v_add_u32_e32 v3, v6, v3
	v_mul_hi_u32 v3, v7, v3
	v_mul_lo_u32 v5, v3, v4
	v_sub_u32_e32 v5, v7, v5
	v_add_u32_e32 v6, 1, v3
	v_cmp_ge_u32_e32 vcc, v5, v4
	s_nop 1
	v_cndmask_b32_e32 v3, v3, v6, vcc
	v_sub_u32_e32 v6, v5, v4
	v_cndmask_b32_e32 v5, v5, v6, vcc
	v_add_u32_e32 v6, 1, v3
	v_cmp_ge_u32_e32 vcc, v5, v4
	v_add_u32_e32 v5, 1, v7
	s_nop 0
	v_cndmask_b32_e32 v3, v3, v6, vcc
	v_mul_lo_u32 v6, v4, v3
	v_add_u32_e32 v4, v6, v4
	v_cmp_ne_u32_e32 vcc, v5, v4
	s_and_saveexec_b64 s[8:9], vcc
	s_xor_b64 s[18:19], exec, s[8:9]
	s_cbranch_execz .LBB0_1386
	v_readlane_b32 s8, v255, 10
	v_readlane_b32 s9, v255, 11
	s_waitcnt lgkmcnt(0)
	s_nop 3
	global_load_dword v2, v181, s[8:9] sc1
	s_waitcnt vmcnt(0)
	v_cmp_eq_u32_e32 vcc, v2, v3
	s_and_saveexec_b64 s[22:23], vcc
	s_cbranch_execz .LBB0_1385
	s_mov_b32 s7, 1
	s_mov_b64 s[24:25], 0
	s_branch .LBB0_1376

.LBB0_1378:
	v_readlane_b32 s8, v255, 10
	v_readlane_b32 s9, v255, 11
	s_add_i32 s7, s7, 1
	s_mov_b64 s[30:31], -1
	s_nop 2
	global_load_dword v2, v181, s[8:9] sc1
	s_waitcnt vmcnt(0)
	v_cmp_ne_u32_e32 vcc, v2, v3
	s_orn2_b64 s[28:29], vcc, exec
	s_branch .LBB0_1375

.LBB0_1517:
	s_or_b64 exec, exec, s[10:11]
	v_cvt_f32_u32_e32 v6, v4
	s_waitcnt vmcnt(0)
	v_readfirstlane_b32 s6, v5
	v_sub_u32_e32 v5, 0, v4
	v_rcp_iflag_f32_e32 v6, v6
	v_add_u32_e32 v7, s6, v3
	v_mul_f32_e32 v6, 0x4f7ffffe, v6
	v_cvt_u32_f32_e32 v6, v6
	v_mul_lo_u32 v3, v5, v6
	v_mul_hi_u32 v3, v6, v3
	v_add_u32_e32 v3, v6, v3
	v_mul_hi_u32 v3, v7, v3
	v_mul_lo_u32 v5, v3, v4
	v_sub_u32_e32 v5, v7, v5
	v_add_u32_e32 v6, 1, v3
	v_cmp_ge_u32_e32 vcc, v5, v4
	s_nop 1
	v_cndmask_b32_e32 v3, v3, v6, vcc
	v_sub_u32_e32 v6, v5, v4
	v_cndmask_b32_e32 v5, v5, v6, vcc
	v_add_u32_e32 v6, 1, v3
	v_cmp_ge_u32_e32 vcc, v5, v4
	v_add_u32_e32 v5, 1, v7
	s_nop 0
	v_cndmask_b32_e32 v3, v3, v6, vcc
	v_mul_lo_u32 v6, v4, v3
	v_add_u32_e32 v4, v6, v4
	v_cmp_ne_u32_e32 vcc, v5, v4
	s_and_saveexec_b64 s[6:7], vcc
	s_xor_b64 s[10:11], exec, s[6:7]
	s_cbranch_execz .LBB0_1531
	v_readlane_b32 s6, v255, 10
	v_readlane_b32 s7, v255, 11
	s_waitcnt lgkmcnt(0)
	s_nop 3
	global_load_dword v2, v181, s[6:7] sc1
	s_waitcnt vmcnt(0)
	v_cmp_eq_u32_e32 vcc, v2, v3
	s_and_saveexec_b64 s[14:15], vcc
	s_cbranch_execz .LBB0_1530
	s_mov_b32 s6, 1
	s_mov_b64 s[18:19], 0
	s_branch .LBB0_1521

.LBB0_1523:
	v_readlane_b32 s8, v255, 10
	v_readlane_b32 s9, v255, 11
	s_add_i32 s6, s6, 1
	s_mov_b64 s[26:27], -1
	s_nop 2
	global_load_dword v2, v181, s[8:9] sc1
	s_waitcnt vmcnt(0)
	v_cmp_ne_u32_e32 vcc, v2, v3
	s_orn2_b64 s[24:25], vcc, exec
	s_branch .LBB0_1520

.LBB0_2412:
	s_or_b64 exec, exec, s[2:3]
	v_cvt_f32_u32_e32 v4, v2
	s_waitcnt vmcnt(0)
	v_readfirstlane_b32 s2, v3
	v_sub_u32_e32 v3, 0, v2
	v_rcp_iflag_f32_e32 v4, v4
	v_add_u32_e32 v5, s2, v1
	v_mul_f32_e32 v4, 0x4f7ffffe, v4
	v_cvt_u32_f32_e32 v4, v4
	v_mul_lo_u32 v1, v3, v4
	v_mul_hi_u32 v1, v4, v1
	v_add_u32_e32 v1, v4, v1
	v_mul_hi_u32 v1, v5, v1
	v_mul_lo_u32 v3, v1, v2
	v_sub_u32_e32 v3, v5, v3
	v_add_u32_e32 v4, 1, v1
	v_cmp_ge_u32_e32 vcc, v3, v2
	s_nop 1
	v_cndmask_b32_e32 v1, v1, v4, vcc
	v_sub_u32_e32 v4, v3, v2
	v_cndmask_b32_e32 v3, v3, v4, vcc
	v_add_u32_e32 v4, 1, v1
	v_cmp_ge_u32_e32 vcc, v3, v2
	v_add_u32_e32 v3, 1, v5
	s_nop 0
	v_cndmask_b32_e32 v1, v1, v4, vcc
	v_mul_lo_u32 v4, v2, v1
	v_add_u32_e32 v2, v4, v2
	v_cmp_ne_u32_e32 vcc, v3, v2
	s_and_saveexec_b64 s[2:3], vcc
	s_xor_b64 s[2:3], exec, s[2:3]
	s_cbranch_execz .LBB0_2426
	v_readlane_b32 s4, v255, 10
	s_waitcnt lgkmcnt(0)
	v_mov_b32_e32 v0, 0
	v_readlane_b32 s5, v255, 11
	s_nop 4
	global_load_dword v2, v0, s[4:5] sc1
	s_waitcnt vmcnt(0)
	v_cmp_eq_u32_e32 vcc, v2, v1
	s_and_saveexec_b64 s[4:5], vcc
	s_cbranch_execz .LBB0_2425
	s_mov_b32 s16, 1
	s_mov_b64 s[6:7], 0
	s_branch .LBB0_2416

.LBB0_2418:
	v_readlane_b32 s10, v255, 10
	v_readlane_b32 s11, v255, 11
	s_add_i32 s16, s16, 1
	s_mov_b64 s[12:13], -1
	s_nop 2
	global_load_dword v2, v0, s[10:11] sc1
	s_waitcnt vmcnt(0)
	v_cmp_ne_u32_e32 vcc, v2, v1
	s_orn2_b64 s[10:11], vcc, exec
	s_branch .LBB0_2415
